# combined: uneven v-row conv split, scalar-base o stores and shorter loop edge in the scan, SGU row loads issued early
# speedup vs baseline: 1.0082x; 1.0081x over previous
.Lscan_compute:
	s_mul_i32 s11, s11, 0x12000
	s_add_i32 s6, s11, 0
	v_add_u32_e32 v0, s6, v58
	v_add_u32_e32 v2, s6, v59
	v_add_u32_e32 v3, s6, v60
	v_add_u32_e32 v142, s6, v61
	ds_read_b128 v[62:65], v0
	ds_read_b128 v[66:69], v0 offset:4096
	ds_read_b128 v[70:73], v2
	ds_read_b128 v[74:77], v2 offset:4096
	ds_read_b128 v[78:81], v3
	ds_read_b128 v[82:85], v3 offset:4096
	ds_read_b128 v[86:89], v142
	ds_read_b128 v[90:93], v142 offset:4096
	ds_read_b128 v[94:97], v0 offset:8192
	ds_read_b128 v[98:101], v0 offset:12288
	ds_read_b128 v[102:105], v2 offset:8192
	ds_read_b128 v[106:109], v2 offset:12288
	ds_read_b128 v[110:113], v3 offset:8192
	ds_read_b128 v[114:117], v3 offset:12288
	ds_read_b128 v[118:121], v142 offset:8192
	ds_read_b128 v[122:125], v142 offset:12288
	ds_read_b128 v[126:129], v0 offset:16384
	ds_read_b128 v[130:133], v0 offset:20480
	ds_read_b128 v[134:137], v2 offset:16384
	ds_read_b128 v[138:141], v2 offset:20480
	ds_read_b128 v[146:149], v3 offset:16384
	ds_read_b128 v[154:157], v3 offset:20480
	ds_read_b128 v[162:165], v142 offset:16384
	ds_read_b128 v[166:169], v142 offset:20480
	ds_read_b128 v[170:173], v0 offset:24576
	ds_read_b128 v[174:177], v0 offset:28672
	ds_read_b128 v[178:181], v2 offset:24576
	ds_read_b128 v[182:185], v2 offset:28672
	ds_read_b128 v[186:189], v3 offset:24576
	ds_read_b128 v[190:193], v3 offset:28672
	ds_read_b128 v[194:197], v142 offset:24576
	ds_read_b128 v[198:201], v142 offset:28672
	v_cvt_pk_bf16_f32 v202, v12, v13
	v_cvt_pk_bf16_f32 v203, v14, v15
	v_cvt_pk_bf16_f32 v204, v4, v5
	v_cvt_pk_bf16_f32 v205, v6, v7
	v_cvt_pk_bf16_f32 v206, v8, v9
	v_cvt_pk_bf16_f32 v207, v10, v11
	v_cvt_pk_bf16_f32 v208, v16, v17
	v_cvt_pk_bf16_f32 v209, v18, v19
	v_cvt_pk_bf16_f32 v210, v20, v21
	v_cvt_pk_bf16_f32 v211, v22, v23
	v_cvt_pk_bf16_f32 v212, v24, v25
	v_cvt_pk_bf16_f32 v213, v26, v27
	v_cvt_pk_bf16_f32 v222, v28, v29
	v_cvt_pk_bf16_f32 v223, v30, v31
	v_cvt_pk_bf16_f32 v224, v32, v33
	v_cvt_pk_bf16_f32 v225, v34, v35
	s_waitcnt lgkmcnt(14)
	v_mfma_f32_16x16x32_bf16 v[62:65], v[62:65], v[202:205], 0
	v_add3_u32 v0, s6, v56, v57
	v_add_u32_e32 v145, s6, v55
	v_add_u32_e32 v159, s6, v54
	v_mfma_f32_16x16x32_bf16 v[66:69], v[66:69], v[202:205], 0
	ds_read2st64_b32 v[2:3], v0 offset0:224 offset1:225
	ds_read2st64_b32 v[142:143], v0 offset0:226 offset1:227
	v_mfma_f32_16x16x32_bf16 v[62:65], v[70:73], v[206:209], v[62:65]
	v_mfma_f32_16x16x32_bf16 v[66:69], v[74:77], v[206:209], v[66:69]
	v_mfma_f32_16x16x32_bf16 v[70:73], v[94:97], v[202:205], 0
	v_mfma_f32_16x16x32_bf16 v[62:65], v[78:81], v[210:213], v[62:65]
	ds_read_b128 v[78:81], v145 offset:49152
	v_mfma_f32_16x16x32_bf16 v[66:69], v[82:85], v[210:213], v[66:69]
	v_mfma_f32_16x16x32_bf16 v[74:77], v[98:101], v[202:205], 0
	v_mfma_f32_16x16x32_bf16 v[70:73], v[102:105], v[206:209], v[70:73]
	v_add_u32_e32 v102, 0xe000, v0
	v_mfma_f32_16x16x32_bf16 v[62:65], v[86:89], v[222:225], v[62:65]
	v_mfma_f32_16x16x32_bf16 v[66:69], v[90:93], v[222:225], v[66:69]
	v_mfma_f32_16x16x32_bf16 v[74:77], v[106:109], v[206:209], v[74:77]
	ds_read_b128 v[82:85], v159 offset:49152
	ds_read2st64_b32 v[226:227], v0 offset0:240 offset1:241
	ds_read2st64_b32 v[228:229], v0 offset0:242 offset1:243
	ds_read_b128 v[86:89], v145 offset:51200
	ds_read_b128 v[90:93], v159 offset:51200
	ds_read2st64_b32 v[230:231], v102 offset0:32 offset1:33
	ds_read2st64_b32 v[232:233], v102 offset0:34 offset1:35
	ds_read_b128 v[94:97], v145 offset:53248
	ds_read_b128 v[98:101], v159 offset:53248
	ds_read2st64_b32 v[234:235], v102 offset0:48 offset1:49
	ds_read2st64_b32 v[236:237], v102 offset0:50 offset1:51
	ds_read_b128 v[102:105], v145 offset:55296
	ds_read_b128 v[106:109], v159 offset:55296
	v_mfma_f32_16x16x32_bf16 v[70:73], v[110:113], v[210:213], v[70:73]
	v_mfma_f32_16x16x32_bf16 v[74:77], v[114:117], v[210:213], v[74:77]
	v_mfma_f32_16x16x32_bf16 v[70:73], v[118:121], v[222:225], v[70:73]
	v_mfma_f32_16x16x32_bf16 v[74:77], v[122:125], v[222:225], v[74:77]
	v_mfma_f32_16x16x32_bf16 v[110:113], v[126:129], v[202:205], 0
	v_mfma_f32_16x16x32_bf16 v[114:117], v[130:133], v[202:205], 0
	s_waitcnt lgkmcnt(14)
	v_mfma_f32_16x16x32_bf16 v[118:121], v[170:173], v[202:205], 0
	v_mfma_f32_16x16x32_bf16 v[122:125], v[174:177], v[202:205], 0
	v_mfma_f32_16x16x32_bf16 v[110:113], v[134:137], v[206:209], v[110:113]
	v_mfma_f32_16x16x32_bf16 v[114:117], v[138:141], v[206:209], v[114:117]
	v_mfma_f32_16x16x32_bf16 v[118:121], v[178:181], v[206:209], v[118:121]
	v_mfma_f32_16x16x32_bf16 v[122:125], v[182:185], v[206:209], v[122:125]
	v_mfma_f32_16x16x32_bf16 v[110:113], v[146:149], v[210:213], v[110:113]
	v_mfma_f32_16x16x32_bf16 v[114:117], v[154:157], v[210:213], v[114:117]
	v_mfma_f32_16x16x32_bf16 v[118:121], v[186:189], v[210:213], v[118:121]
	v_mfma_f32_16x16x32_bf16 v[122:125], v[190:193], v[210:213], v[122:125]
	v_mfma_f32_16x16x32_bf16 v[110:113], v[162:165], v[222:225], v[110:113]
	v_mfma_f32_16x16x32_bf16 v[114:117], v[166:169], v[222:225], v[114:117]
	v_mfma_f32_16x16x32_bf16 v[118:121], v[194:197], v[222:225], v[118:121]
	v_mfma_f32_16x16x32_bf16 v[122:125], v[198:201], v[222:225], v[122:125]
	ds_read_b128 v[126:129], v145 offset:32768
	ds_read_b128 v[130:133], v159 offset:32768
	ds_read_b128 v[134:137], v145 offset:34816
	ds_read_b128 v[138:141], v159 offset:34816
	ds_read_b128 v[146:149], v145 offset:36864
	ds_read_b128 v[154:157], v159 offset:36864
	ds_read_b128 v[162:165], v145 offset:38912
	ds_read_b128 v[166:169], v159 offset:38912
	ds_read_b128 v[170:173], v145 offset:40960
	ds_read_b128 v[174:177], v159 offset:40960
	ds_read_b128 v[178:181], v145 offset:43008
	ds_read_b128 v[182:185], v159 offset:43008
	ds_read_b128 v[186:189], v145 offset:45056
	ds_read_b128 v[190:193], v159 offset:45056
	ds_read_b128 v[194:197], v145 offset:47104
	ds_read_b128 v[198:201], v159 offset:47104
	v_pk_add_f32 v[2:3], v[2:3], v[62:63] neg_lo:[0,1] neg_hi:[0,1]
	v_pk_add_f32 v[64:65], v[142:143], v[64:65] neg_lo:[0,1] neg_hi:[0,1]
	s_waitcnt lgkmcnt(14)
	v_pk_add_f32 v[66:67], v[226:227], v[66:67] neg_lo:[0,1] neg_hi:[0,1]
	v_pk_add_f32 v[68:69], v[228:229], v[68:69] neg_lo:[0,1] neg_hi:[0,1]
	v_pk_add_f32 v[70:71], v[230:231], v[70:71] neg_lo:[0,1] neg_hi:[0,1]
	v_cvt_pk_bf16_f32 v62, v2, v3
	v_cvt_pk_bf16_f32 v63, v64, v65
	v_cvt_pk_bf16_f32 v64, v66, v67
	v_cvt_pk_bf16_f32 v65, v68, v69
	v_pk_add_f32 v[142:143], v[232:233], v[72:73] neg_lo:[0,1] neg_hi:[0,1]
	v_cvt_pk_bf16_f32 v66, v70, v71
	v_mfma_f32_16x16x32_bf16 v[70:73], v[78:81], v[62:65], v[110:113]
	v_readlane_b32 s6, v37, s10
	v_pk_add_f32 v[74:75], v[234:235], v[74:75] neg_lo:[0,1] neg_hi:[0,1]
	v_pk_add_f32 v[76:77], v[236:237], v[76:77] neg_lo:[0,1] neg_hi:[0,1]
	v_pk_mul_f32 v[6:7], v[6:7], s[6:7] op_sel_hi:[1,0]
	v_pk_mul_f32 v[4:5], v[4:5], s[6:7] op_sel_hi:[1,0]
	v_cvt_pk_bf16_f32 v67, v142, v143
	v_cvt_pk_bf16_f32 v68, v74, v75
	v_cvt_pk_bf16_f32 v69, v76, v77
	s_waitcnt lgkmcnt(13)
	v_mfma_f32_16x16x32_bf16 v[2:5], v[134:137], v[62:65], v[4:7]
	v_mul_f32_e64 v14, v14, s6
	v_mul_f32_e64 v15, v15, s6
	v_pk_mul_f32 v[12:13], v[12:13], s[6:7] op_sel_hi:[1,0]
	v_pk_mul_f32 v[10:11], v[10:11], s[6:7] op_sel_hi:[1,0]
	v_mfma_f32_16x16x32_bf16 v[70:73], v[82:85], v[66:69], v[70:73]
	v_mul_f32_e64 v8, v8, s6
	v_mul_f32_e64 v9, v9, s6
	v_pk_mul_f32 v[18:19], v[18:19], s[6:7] op_sel_hi:[1,0]
	v_pk_mul_f32 v[16:17], v[16:17], s[6:7] op_sel_hi:[1,0]
	v_mfma_f32_16x16x32_bf16 v[74:77], v[86:89], v[62:65], v[114:117]
	v_mul_f32_e64 v22, v22, s6
	v_mul_f32_e64 v23, v23, s6
	s_nop 0
	v_cvt_pk_bf16_f32 v0, v70, s0
	v_pk_mul_f32 v[20:21], v[20:21], s[6:7] op_sel_hi:[1,0]
	s_waitcnt lgkmcnt(12)
	v_mfma_f32_16x16x32_bf16 v[4:7], v[138:141], v[66:69], v[2:5]
	v_mul_f32_e64 v26, v26, s6
	v_mul_f32_e64 v27, v27, s6
	v_pk_mul_f32 v[24:25], v[24:25], s[6:7] op_sel_hi:[1,0]
	v_pk_mul_f32 v[30:31], v[30:31], s[6:7] op_sel_hi:[1,0]
	v_add_u32_e32 v70, 0x1000, v38
	v_pk_mul_f32 v[28:29], v[28:29], s[6:7] op_sel_hi:[1,0]
	v_pk_mul_f32 v[34:35], v[34:35], s[6:7] op_sel_hi:[1,0]
	v_pk_mul_f32 v[32:33], v[32:33], s[6:7] op_sel_hi:[1,0]
	global_store_short v38, v0, s[2:3]
	v_cvt_pk_bf16_f32 v0, v71, s0
	global_store_short v70, v0, s[2:3] offset:2048
	v_add_u32_e32 v70, 0x3000, v38
	v_mfma_f32_16x16x32_bf16 v[74:77], v[90:93], v[66:69], v[74:77]
	v_cvt_pk_bf16_f32 v0, v72, s0
	global_store_short v70, v0, s[2:3]
	v_add_u32_e32 v70, 0x4000, v38
	v_cvt_pk_bf16_f32 v0, v73, s0
	global_store_short v70, v0, s[2:3] offset:2048
	v_add_u32_e32 v70, 0x18000, v38
	v_mfma_f32_16x16x32_bf16 v[78:81], v[94:97], v[62:65], v[118:121]
	v_cvt_pk_bf16_f32 v0, v74, s0
	global_store_short v70, v0, s[2:3]
	v_add_u32_e32 v70, 0x19000, v38
	v_mfma_f32_16x16x32_bf16 v[82:85], v[102:105], v[62:65], v[122:125]
	v_cvt_pk_bf16_f32 v0, v75, s0
	global_store_short v70, v0, s[2:3] offset:2048
	v_cvt_pk_bf16_f32 v0, v76, s0
	v_mfma_f32_16x16x32_bf16 v[12:15], v[126:129], v[62:65], v[12:15]
	s_waitcnt lgkmcnt(11)
	v_mfma_f32_16x16x32_bf16 v[8:11], v[146:149], v[62:65], v[8:11]
	s_waitcnt lgkmcnt(9)
	v_mfma_f32_16x16x32_bf16 v[16:19], v[162:165], v[62:65], v[16:19]
	s_waitcnt lgkmcnt(7)
	v_mfma_f32_16x16x32_bf16 v[20:23], v[170:173], v[62:65], v[20:23]
	s_waitcnt lgkmcnt(5)
	v_mfma_f32_16x16x32_bf16 v[24:27], v[178:181], v[62:65], v[24:27]
	s_waitcnt lgkmcnt(3)
	v_mfma_f32_16x16x32_bf16 v[28:31], v[186:189], v[62:65], v[28:31]
	s_waitcnt lgkmcnt(1)
	v_mfma_f32_16x16x32_bf16 v[32:35], v[194:197], v[62:65], v[32:35]
	v_add_u32_e32 v62, 0x1b000, v38
	v_mfma_f32_16x16x32_bf16 v[78:81], v[98:101], v[66:69], v[78:81]
	global_store_short v62, v0, s[2:3]
	v_add_u32_e32 v62, 0x1c000, v38
	v_cvt_pk_bf16_f32 v0, v77, s0
	global_store_short v62, v0, s[2:3] offset:2048
	v_add_u32_e32 v62, 0x30000, v38
	v_cvt_pk_bf16_f32 v0, v78, s0
	global_store_short v62, v0, s[2:3]
	v_add_u32_e32 v62, 0x31000, v38
	v_cvt_pk_bf16_f32 v0, v79, s0
	global_store_short v62, v0, s[2:3] offset:2048
	v_add_u32_e32 v62, 0x33000, v38
	v_mfma_f32_16x16x32_bf16 v[82:85], v[106:109], v[66:69], v[82:85]
	v_cvt_pk_bf16_f32 v0, v80, s0
	global_store_short v62, v0, s[2:3]
	v_add_u32_e32 v62, 0x34000, v38
	v_cvt_pk_bf16_f32 v0, v81, s0
	global_store_short v62, v0, s[2:3] offset:2048
	v_add_u32_e32 v62, 0x48000, v38
	v_cvt_pk_bf16_f32 v0, v82, s0
	global_store_short v62, v0, s[2:3]
	v_add_u32_e32 v62, 0x49000, v38
	v_cvt_pk_bf16_f32 v0, v83, s0
	global_store_short v62, v0, s[2:3] offset:2048
	v_add_u32_e32 v62, 0x4b000, v38
	v_cvt_pk_bf16_f32 v0, v84, s0
	v_add_u32_e32 v2, 0x4c000, v38
	global_store_short v62, v0, s[2:3]
	v_cvt_pk_bf16_f32 v0, v85, s0
	v_mfma_f32_16x16x32_bf16 v[12:15], v[130:133], v[66:69], v[12:15]
	global_store_short v2, v0, s[2:3] offset:2048
	s_waitcnt vmcnt(16) lgkmcnt(0)
	s_barrier
	v_mfma_f32_16x16x32_bf16 v[8:11], v[154:157], v[66:69], v[8:11]
	v_mfma_f32_16x16x32_bf16 v[16:19], v[166:169], v[66:69], v[16:19]
	v_mfma_f32_16x16x32_bf16 v[20:23], v[174:177], v[66:69], v[20:23]
	v_mfma_f32_16x16x32_bf16 v[24:27], v[182:185], v[66:69], v[24:27]
	v_mfma_f32_16x16x32_bf16 v[28:31], v[190:193], v[66:69], v[28:31]
	s_waitcnt lgkmcnt(0)
	v_mfma_f32_16x16x32_bf16 v[32:35], v[198:201], v[66:69], v[32:35]
	s_mov_b64 s[6:7], 0x60000
	s_add_i32 s10, s10, 1
	v_lshl_add_u64 v[38:39], v[38:39], 0, s[6:7]
	s_and_b32 s11, s10, 1
	s_cmp_lg_u32 s10, 63
	s_cbranch_scc1 .Lscan_compute
	s_branch .LBB0_163
